# attention steady loop: LDS-DMA destination written straight into m0 by the add (one SALU move less per DMA, 4 per loop iteration)
# baseline (speedup 1.0000x reference)
.LBB0_148:
	v_add_u32_e32 v168, s6, v221
	ds_read_b64_tr_b16 v[164:165], v168 offset:24576
	ds_read_b64_tr_b16 v[166:167], v168 offset:25088
	v_mfma_f32_32x32x16_bf16 v[64:79], v[156:159], v[116:119], v[64:79]
	v_add_f32_e32 v104, v80, v81
	v_add_f32_e32 v104, v82, v104
	v_add_f32_e32 v104, v83, v104
	v_add_f32_e32 v104, v84, v104
	v_add_f32_e32 v104, v85, v104
	v_cvt_pk_bf16_f32 v124, v80, v81
	v_cvt_pk_bf16_f32 v125, v82, v83
	ds_read_b64_tr_b16 v[160:161], v168 offset:28672
	ds_read_b64_tr_b16 v[162:163], v168 offset:29184
	v_mfma_f32_32x32x16_bf16 v[48:63], v[152:155], v[116:119], v[48:63]
	v_add_f32_e32 v80, v86, v104
	v_add_f32_e32 v80, v87, v80
	v_add_f32_e32 v80, v88, v80
	v_add_f32_e32 v80, v89, v80
	v_cvt_pk_bf16_f32 v126, v84, v85
	v_cvt_pk_bf16_f32 v127, v86, v87
	ds_read_b64_tr_b16 v[152:153], v168 offset:25600
	ds_read_b64_tr_b16 v[154:155], v168 offset:26112
	v_mfma_f32_32x32x16_bf16 v[64:79], v[148:151], v[108:111], v[64:79]
	v_add_f32_e32 v80, v90, v80
	v_add_f32_e32 v80, v91, v80
	v_add_f32_e32 v80, v92, v80
	v_add_f32_e32 v80, v93, v80
	v_cvt_pk_bf16_f32 v120, v88, v89
	v_cvt_pk_bf16_f32 v121, v90, v91
	ds_read_b64_tr_b16 v[148:149], v168 offset:29696
	ds_read_b64_tr_b16 v[150:151], v168 offset:30208
	v_mfma_f32_32x32x16_bf16 v[48:63], v[144:147], v[108:111], v[48:63]
	v_add_f32_e32 v80, v94, v80
	v_add_f32_e32 v80, v95, v80
	v_add_f32_e32 v80, v32, v80
	v_add_f32_e32 v80, v33, v80
	v_cvt_pk_bf16_f32 v122, v92, v93
	v_cvt_pk_bf16_f32 v123, v94, v95
	ds_read_b64_tr_b16 v[156:157], v168 offset:26624
	ds_read_b64_tr_b16 v[158:159], v168 offset:27136
	v_mfma_f32_32x32x16_bf16 v[64:79], v[140:143], v[100:103], v[64:79]
	v_add_f32_e32 v80, v34, v80
	v_add_f32_e32 v80, v35, v80
	v_add_f32_e32 v80, v36, v80
	v_add_f32_e32 v80, v37, v80
	v_cvt_pk_bf16_f32 v112, v32, v33
	v_cvt_pk_bf16_f32 v113, v34, v35
	ds_read_b64_tr_b16 v[144:145], v168 offset:30720
	ds_read_b64_tr_b16 v[146:147], v168 offset:31232
	v_mfma_f32_32x32x16_bf16 v[48:63], v[132:135], v[100:103], v[48:63]
	v_add_f32_e32 v32, v38, v80
	v_add_f32_e32 v32, v39, v32
	v_add_f32_e32 v32, v40, v32
	v_add_f32_e32 v32, v41, v32
	v_cvt_pk_bf16_f32 v114, v36, v37
	v_cvt_pk_bf16_f32 v115, v38, v39
	ds_read_b64_tr_b16 v[140:141], v168 offset:27648
	ds_read_b64_tr_b16 v[142:143], v168 offset:28160
	v_mfma_f32_32x32x16_bf16 v[64:79], v[136:139], v[96:99], v[64:79]
	v_add_f32_e32 v32, v42, v32
	v_add_f32_e32 v32, v43, v32
	v_add_f32_e32 v32, v44, v32
	v_add_f32_e32 v32, v45, v32
	v_cvt_pk_bf16_f32 v104, v40, v41
	v_cvt_pk_bf16_f32 v105, v42, v43
	ds_read_b64_tr_b16 v[132:133], v168 offset:31744
	ds_read_b64_tr_b16 v[134:135], v168 offset:32256
	v_mfma_f32_32x32x16_bf16 v[48:63], v[128:131], v[96:99], v[48:63]
	v_add_f32_e32 v32, v46, v32
	v_add_f32_e32 v32, v47, v32
	v_add_f32_e32 v34, 0, v32
	v_cvt_pk_bf16_f32 v106, v44, v45
	v_cvt_pk_bf16_f32 v107, v46, v47
	v_lshl_add_u64 v[32:33], v[178:179], 0, s[90:91]
	s_add_i32 m0, s41, s18
	s_nop 0
	global_load_lds_dwordx4 v[32:33], off
	v_lshl_add_u64 v[32:33], v[176:177], 0, s[90:91]
	s_add_i32 m0, s28, s19
	s_nop 0
	global_load_lds_dwordx4 v[32:33], off
	v_max_f32_e32 v32, v64, v65
	v_max3_f32 v33, v66, v67, v49
	v_max3_f32 v32, v32, v48, v50
	v_max3_f32 v32, v32, v51, v68
	v_max3_f32 v33, v33, v70, v71
	v_max3_f32 v32, v32, v69, v52
	v_max3_f32 v33, v33, v54, v55
	v_max3_f32 v32, v32, v53, v72
	v_max3_f32 v33, v33, v74, v75
	v_max3_f32 v32, v32, v73, v56
	v_max3_f32 v33, v33, v58, v59
	v_max3_f32 v32, v32, v57, v76
	v_max3_f32 v33, v33, v78, v79
	v_max3_f32 v32, v32, v77, v60
	v_max3_f32 v33, v33, v62, v63
	v_max3_f32 v32, v32, v61, v33
	v_mov_b32_e32 v33, v32
	s_nop 1
	v_permlane32_swap_b32_e32 v32, v33
	v_max_f32_e32 v32, v32, v33
	v_cmp_lt_f32_e32 vcc, s47, v32
	s_cmp_lg_u64 vcc, 0
	v_add_f32_e32 v181, v222, v34
	s_cselect_b64 s[6:7], -1, 0
	s_cbranch_vccnz .LBB0_156

.LBB0_151:
	s_add_i32 s6, s28, 0x2000
	s_cmpk_lg_i32 s28, 0x4000
	s_cselect_b32 s22, s6, 0
	v_add_u32_e32 v182, s41, v221
	ds_read_b64_tr_b16 v[144:145], v182 offset:24576
	ds_read_b64_tr_b16 v[146:147], v182 offset:25088
	v_mfma_f32_32x32x16_bf16 v[80:95], v[168:171], v[116:119], v[80:95]
	v_add_f32_e32 v104, v64, v65
	v_add_f32_e32 v104, v66, v104
	v_add_f32_e32 v104, v67, v104
	v_add_f32_e32 v104, v68, v104
	v_add_f32_e32 v104, v69, v104
	v_cvt_pk_bf16_f32 v124, v64, v65
	v_cvt_pk_bf16_f32 v125, v66, v67
	ds_read_b64_tr_b16 v[140:141], v182 offset:28672
	ds_read_b64_tr_b16 v[142:143], v182 offset:29184
	v_mfma_f32_32x32x16_bf16 v[32:47], v[128:131], v[116:119], v[32:47]
	v_add_f32_e32 v64, v70, v104
	v_add_f32_e32 v64, v71, v64
	v_add_f32_e32 v64, v72, v64
	v_add_f32_e32 v64, v73, v64
	v_cvt_pk_bf16_f32 v126, v68, v69
	v_cvt_pk_bf16_f32 v127, v70, v71
	ds_read_b64_tr_b16 v[132:133], v182 offset:25600
	ds_read_b64_tr_b16 v[134:135], v182 offset:26112
	v_mfma_f32_32x32x16_bf16 v[80:95], v[164:167], v[108:111], v[80:95]
	v_add_f32_e32 v64, v74, v64
	v_add_f32_e32 v64, v75, v64
	v_add_f32_e32 v64, v76, v64
	v_add_f32_e32 v64, v77, v64
	v_cvt_pk_bf16_f32 v120, v72, v73
	v_cvt_pk_bf16_f32 v121, v74, v75
	ds_read_b64_tr_b16 v[128:129], v182 offset:29696
	ds_read_b64_tr_b16 v[130:131], v182 offset:30208
	v_mfma_f32_32x32x16_bf16 v[32:47], v[152:155], v[108:111], v[32:47]
	v_add_f32_e32 v64, v78, v64
	v_add_f32_e32 v64, v79, v64
	v_add_f32_e32 v64, v48, v64
	v_add_f32_e32 v64, v49, v64
	v_cvt_pk_bf16_f32 v122, v76, v77
	v_cvt_pk_bf16_f32 v123, v78, v79
	ds_read_b64_tr_b16 v[172:173], v182 offset:26624
	ds_read_b64_tr_b16 v[174:175], v182 offset:27136
	v_mfma_f32_32x32x16_bf16 v[80:95], v[160:163], v[100:103], v[80:95]
	v_add_f32_e32 v64, v50, v64
	v_add_f32_e32 v64, v51, v64
	v_add_f32_e32 v64, v52, v64
	v_add_f32_e32 v64, v53, v64
	v_cvt_pk_bf16_f32 v112, v48, v49
	v_cvt_pk_bf16_f32 v113, v50, v51
	ds_read_b64_tr_b16 v[168:169], v182 offset:30720
	ds_read_b64_tr_b16 v[170:171], v182 offset:31232
	v_mfma_f32_32x32x16_bf16 v[32:47], v[148:151], v[100:103], v[32:47]
	v_add_f32_e32 v48, v54, v64
	v_add_f32_e32 v48, v55, v48
	v_add_f32_e32 v48, v56, v48
	v_add_f32_e32 v48, v57, v48
	v_cvt_pk_bf16_f32 v114, v52, v53
	v_cvt_pk_bf16_f32 v115, v54, v55
	ds_read_b64_tr_b16 v[164:165], v182 offset:27648
	ds_read_b64_tr_b16 v[166:167], v182 offset:28160
	v_mfma_f32_32x32x16_bf16 v[80:95], v[156:159], v[96:99], v[80:95]
	v_add_f32_e32 v48, v58, v48
	v_add_f32_e32 v48, v59, v48
	v_add_f32_e32 v48, v60, v48
	v_add_f32_e32 v48, v61, v48
	v_cvt_pk_bf16_f32 v104, v56, v57
	v_cvt_pk_bf16_f32 v105, v58, v59
	ds_read_b64_tr_b16 v[160:161], v182 offset:31744
	ds_read_b64_tr_b16 v[162:163], v182 offset:32256
	v_mfma_f32_32x32x16_bf16 v[32:47], v[136:139], v[96:99], v[32:47]
	v_add_f32_e32 v48, v62, v48
	v_add_f32_e32 v48, v63, v48
	v_add_f32_e32 v48, 0, v48
	v_cvt_pk_bf16_f32 v106, v60, v61
	v_cvt_pk_bf16_f32 v107, v62, v63
	v_max_f32_e32 v49, v80, v81
	s_nop 3
	v_max3_f32 v50, v82, v83, v33
	v_max3_f32 v49, v49, v32, v34
	v_max3_f32 v49, v49, v35, v84
	v_max3_f32 v50, v50, v86, v87
	v_max3_f32 v49, v49, v85, v36
	v_max3_f32 v50, v50, v38, v39
	v_max3_f32 v49, v49, v37, v88
	v_max3_f32 v50, v50, v90, v91
	v_max3_f32 v49, v49, v89, v40
	v_max3_f32 v50, v50, v42, v43
	v_max3_f32 v49, v49, v41, v92
	v_max3_f32 v50, v50, v94, v95
	v_max3_f32 v49, v49, v93, v44
	v_max3_f32 v50, v50, v46, v47
	v_add_f32_e32 v222, v181, v48
	v_max3_f32 v48, v49, v45, v50
	v_mov_b32_e32 v49, v48
	s_nop 1
	v_permlane32_swap_b32_e32 v48, v49
	v_max_f32_e32 v49, v49, v49
	v_max_f32_e32 v48, v48, v48
	s_add_i32 m0, s28, s18
	s_nop 0
	global_load_lds_dwordx4 v[178:179], off
	v_max_f32_e32 v48, v48, v49
	s_add_i32 m0, s22, s19
	s_nop 0
	global_load_lds_dwordx4 v[176:177], off
	v_cmp_lt_f32_e32 vcc, s47, v48
	s_cmp_lg_u64 vcc, 0
	s_cselect_b64 s[6:7], -1, 0
	s_cbranch_vccnz .LBB0_159
